# UP: row statistics prefetched in the last K iteration (one dword partial per lane, 8 VGPRs), summed across lane rows by permlane swaps in the epilogue
# speedup vs baseline: 1.0125x; 1.0047x over previous
.LBB0_565:
	s_add_u32 s40, s38, 0xfffc0080
	s_addc_u32 s41, s39, -1
	s_add_i32 s52, 0, 0x10000
	s_cmp_eq_u32 s51, 12
	s_cselect_b32 s43, s21, s41
	s_cselect_b32 s42, s47, s40
	v_add_u32_e32 v0, s52, v141
	s_cselect_b32 s41, s19, s50
	s_cselect_b32 s40, s48, s49
	s_add_i32 s54, 0, 0x14000
	ds_read_b128 v[146:149], v0
	ds_read_b128 v[150:153], v0 offset:1024
	ds_read_b128 v[154:157], v0 offset:2048
	ds_read_b128 v[158:161], v0 offset:3072
	v_add_u32_e32 v0, s54, v141
	ds_read_b128 v[162:165], v0
	ds_read_b128 v[166:169], v0 offset:1024
	ds_read_b128 v[170:173], v0 offset:2048
	ds_read_b128 v[174:177], v0 offset:3072
	s_add_i32 m0, s8, 0xc000
	ds_read_b128 v[178:181], v145
	ds_read_b128 v[182:185], v145 offset:1024
	ds_read_b128 v[186:189], v145 offset:2048
	ds_read_b128 v[190:193], v145 offset:3072
	ds_read_b128 v[194:197], v145 offset:4096
	ds_read_b128 v[208:211], v145 offset:5120
	ds_read_b128 v[212:215], v145 offset:6144
	ds_read_b128 v[216:219], v145 offset:7168
	global_load_lds_dwordx4 v138, s[38:39]
	s_add_i32 m0, s8, 0xe000
	s_nop 0
	global_load_lds_dwordx4 v136, s[38:39]
	s_waitcnt vmcnt(8)
	s_waitcnt lgkmcnt(0)
	s_barrier
	s_setprio 1
	s_waitcnt lgkmcnt(0)
	v_mfma_f32_16x16x32_bf16 v[130:133], v[146:149], v[178:181], v[130:133]
	v_mfma_f32_16x16x32_bf16 v[126:129], v[154:157], v[178:181], v[126:129]
	v_mfma_f32_16x16x32_bf16 v[114:117], v[146:149], v[186:189], v[114:117]
	v_mfma_f32_16x16x32_bf16 v[110:113], v[154:157], v[186:189], v[110:113]
	v_mfma_f32_16x16x32_bf16 v[98:101], v[146:149], v[194:197], v[98:101]
	v_mfma_f32_16x16x32_bf16 v[90:93], v[154:157], v[194:197], v[90:93]
	v_mfma_f32_16x16x32_bf16 v[78:81], v[146:149], v[212:215], v[78:81]
	v_mfma_f32_16x16x32_bf16 v[74:77], v[154:157], v[212:215], v[74:77]
	v_mfma_f32_16x16x32_bf16 v[130:133], v[150:153], v[182:185], v[130:133]
	v_mfma_f32_16x16x32_bf16 v[126:129], v[158:161], v[182:185], v[126:129]
	v_mfma_f32_16x16x32_bf16 v[114:117], v[150:153], v[190:193], v[114:117]
	v_mfma_f32_16x16x32_bf16 v[110:113], v[158:161], v[190:193], v[110:113]
	v_mfma_f32_16x16x32_bf16 v[98:101], v[150:153], v[208:211], v[98:101]
	v_mfma_f32_16x16x32_bf16 v[90:93], v[158:161], v[208:211], v[90:93]
	v_mfma_f32_16x16x32_bf16 v[78:81], v[150:153], v[216:219], v[78:81]
	v_mfma_f32_16x16x32_bf16 v[74:77], v[158:161], v[216:219], v[74:77]
	s_setprio 0
	s_setprio 1
	v_mfma_f32_16x16x32_bf16 v[122:125], v[162:165], v[178:181], v[122:125]
	v_mfma_f32_16x16x32_bf16 v[118:121], v[170:173], v[178:181], v[118:121]
	v_mfma_f32_16x16x32_bf16 v[106:109], v[162:165], v[186:189], v[106:109]
	v_mfma_f32_16x16x32_bf16 v[102:105], v[170:173], v[186:189], v[102:105]
	v_mfma_f32_16x16x32_bf16 v[86:89], v[162:165], v[194:197], v[86:89]
	v_mfma_f32_16x16x32_bf16 v[82:85], v[170:173], v[194:197], v[82:85]
	v_mfma_f32_16x16x32_bf16 v[70:73], v[162:165], v[212:215], v[70:73]
	v_mfma_f32_16x16x32_bf16 v[66:69], v[170:173], v[212:215], v[66:69]
	v_mfma_f32_16x16x32_bf16 v[122:125], v[166:169], v[182:185], v[122:125]
	v_mfma_f32_16x16x32_bf16 v[118:121], v[174:177], v[182:185], v[118:121]
	v_mfma_f32_16x16x32_bf16 v[106:109], v[166:169], v[190:193], v[106:109]
	v_mfma_f32_16x16x32_bf16 v[102:105], v[174:177], v[190:193], v[102:105]
	v_mfma_f32_16x16x32_bf16 v[86:89], v[166:169], v[208:211], v[86:89]
	v_mfma_f32_16x16x32_bf16 v[82:85], v[174:177], v[208:211], v[82:85]
	v_mfma_f32_16x16x32_bf16 v[70:73], v[166:169], v[216:219], v[70:73]
	v_mfma_f32_16x16x32_bf16 v[66:69], v[174:177], v[216:219], v[66:69]
	s_setprio 0
	s_barrier
	s_add_i32 s52, s52, s6
	s_mov_b32 m0, s52
	ds_read_b128 v[178:181], v145 offset:16384
	ds_read_b128 v[182:185], v145 offset:17408
	ds_read_b128 v[186:189], v145 offset:18432
	ds_read_b128 v[190:193], v145 offset:19456
	ds_read_b128 v[194:197], v145 offset:20480
	ds_read_b128 v[208:211], v145 offset:21504
	ds_read_b128 v[212:215], v145 offset:22528
	ds_read_b128 v[216:219], v145 offset:23552
	global_load_lds_dwordx4 v134, s[40:41]
	s_add_i32 m0, s52, 0x2000
	s_add_u32 s52, s40, 0x40000
	s_addc_u32 s53, s41, 0
	s_add_i32 s54, s54, s6
	global_load_lds_dwordx4 v94, s[40:41]
	s_mov_b32 m0, s54
	s_nop 0
	global_load_lds_dwordx4 v134, s[52:53]
	s_add_i32 m0, s54, 0x2000
	s_nop 0
	global_load_lds_dwordx4 v94, s[52:53]
	s_mov_b32 m0, s8
	s_nop 0
	global_load_lds_dwordx4 v134, s[42:43]
	s_mov_b32 m0, s9
	s_nop 0
	global_load_lds_dwordx4 v94, s[42:43]
	s_waitcnt vmcnt(8)
	s_waitcnt lgkmcnt(0)
	s_barrier
	s_setprio 1
	s_waitcnt lgkmcnt(0)
	v_mfma_f32_16x16x32_bf16 v[62:65], v[146:149], v[178:181], v[62:65]
	v_mfma_f32_16x16x32_bf16 v[58:61], v[154:157], v[178:181], v[58:61]
	v_mfma_f32_16x16x32_bf16 v[46:49], v[146:149], v[186:189], v[46:49]
	v_mfma_f32_16x16x32_bf16 v[42:45], v[154:157], v[186:189], v[42:45]
	v_mfma_f32_16x16x32_bf16 v[30:33], v[146:149], v[194:197], v[30:33]
	v_mfma_f32_16x16x32_bf16 v[26:29], v[154:157], v[194:197], v[26:29]
	v_mfma_f32_16x16x32_bf16 v[14:17], v[146:149], v[212:215], v[14:17]
	v_mfma_f32_16x16x32_bf16 v[10:13], v[154:157], v[212:215], v[10:13]
	v_mfma_f32_16x16x32_bf16 v[62:65], v[150:153], v[182:185], v[62:65]
	v_mfma_f32_16x16x32_bf16 v[58:61], v[158:161], v[182:185], v[58:61]
	v_mfma_f32_16x16x32_bf16 v[46:49], v[150:153], v[190:193], v[46:49]
	v_mfma_f32_16x16x32_bf16 v[42:45], v[158:161], v[190:193], v[42:45]
	v_mfma_f32_16x16x32_bf16 v[30:33], v[150:153], v[208:211], v[30:33]
	v_mfma_f32_16x16x32_bf16 v[26:29], v[158:161], v[208:211], v[26:29]
	v_mfma_f32_16x16x32_bf16 v[14:17], v[150:153], v[216:219], v[14:17]
	v_mfma_f32_16x16x32_bf16 v[10:13], v[158:161], v[216:219], v[10:13]
	s_setprio 0
	s_setprio 1
	v_mfma_f32_16x16x32_bf16 v[54:57], v[162:165], v[178:181], v[54:57]
	v_mfma_f32_16x16x32_bf16 v[50:53], v[170:173], v[178:181], v[50:53]
	v_mfma_f32_16x16x32_bf16 v[38:41], v[162:165], v[186:189], v[38:41]
	v_mfma_f32_16x16x32_bf16 v[34:37], v[170:173], v[186:189], v[34:37]
	v_mfma_f32_16x16x32_bf16 v[22:25], v[162:165], v[194:197], v[22:25]
	v_mfma_f32_16x16x32_bf16 v[18:21], v[170:173], v[194:197], v[18:21]
	v_mfma_f32_16x16x32_bf16 v[6:9], v[162:165], v[212:215], v[6:9]
	v_mfma_f32_16x16x32_bf16 v[2:5], v[170:173], v[212:215], v[2:5]
	v_mfma_f32_16x16x32_bf16 v[54:57], v[166:169], v[182:185], v[54:57]
	v_mfma_f32_16x16x32_bf16 v[50:53], v[174:177], v[182:185], v[50:53]
	v_mfma_f32_16x16x32_bf16 v[38:41], v[166:169], v[190:193], v[38:41]
	v_mfma_f32_16x16x32_bf16 v[34:37], v[174:177], v[190:193], v[34:37]
	v_mfma_f32_16x16x32_bf16 v[22:25], v[166:169], v[208:211], v[22:25]
	v_mfma_f32_16x16x32_bf16 v[18:21], v[174:177], v[208:211], v[18:21]
	v_mfma_f32_16x16x32_bf16 v[6:9], v[166:169], v[216:219], v[6:9]
	v_mfma_f32_16x16x32_bf16 v[2:5], v[174:177], v[216:219], v[2:5]
	s_setprio 0
	s_barrier
	s_add_i32 s52, 0, 0x18000
	v_add_u32_e32 v0, s52, v141
	s_add_i32 s53, 0, 0x1c000
	ds_read_b128 v[146:149], v0
	ds_read_b128 v[150:153], v0 offset:1024
	ds_read_b128 v[154:157], v0 offset:2048
	ds_read_b128 v[158:161], v0 offset:3072
	v_add_u32_e32 v0, s53, v141
	ds_read_b128 v[162:165], v0
	ds_read_b128 v[166:169], v0 offset:1024
	ds_read_b128 v[170:173], v0 offset:2048
	ds_read_b128 v[174:177], v0 offset:3072
	s_add_u32 s42, s42, 0x40000
	s_addc_u32 s43, s43, 0
	s_mov_b32 m0, s12
	ds_read_b128 v[178:181], v145 offset:32768
	ds_read_b128 v[182:185], v145 offset:33792
	ds_read_b128 v[186:189], v145 offset:34816
	ds_read_b128 v[190:193], v145 offset:35840
	ds_read_b128 v[194:197], v145 offset:36864
	ds_read_b128 v[208:211], v145 offset:37888
	ds_read_b128 v[212:215], v145 offset:38912
	ds_read_b128 v[216:219], v145 offset:39936
	global_load_lds_dwordx4 v134, s[42:43]
	s_mov_b32 m0, s13
	s_nop 0
	global_load_lds_dwordx4 v94, s[42:43]
	s_waitcnt vmcnt(8)
	s_waitcnt lgkmcnt(0)
	s_barrier
	s_setprio 1
	s_waitcnt lgkmcnt(0)
	v_mfma_f32_16x16x32_bf16 v[130:133], v[146:149], v[178:181], v[130:133]
	v_mfma_f32_16x16x32_bf16 v[126:129], v[154:157], v[178:181], v[126:129]
	v_mfma_f32_16x16x32_bf16 v[114:117], v[146:149], v[186:189], v[114:117]
	v_mfma_f32_16x16x32_bf16 v[110:113], v[154:157], v[186:189], v[110:113]
	v_mfma_f32_16x16x32_bf16 v[98:101], v[146:149], v[194:197], v[98:101]
	v_mfma_f32_16x16x32_bf16 v[90:93], v[154:157], v[194:197], v[90:93]
	v_mfma_f32_16x16x32_bf16 v[78:81], v[146:149], v[212:215], v[78:81]
	v_mfma_f32_16x16x32_bf16 v[74:77], v[154:157], v[212:215], v[74:77]
	v_mfma_f32_16x16x32_bf16 v[130:133], v[150:153], v[182:185], v[130:133]
	v_mfma_f32_16x16x32_bf16 v[126:129], v[158:161], v[182:185], v[126:129]
	v_mfma_f32_16x16x32_bf16 v[114:117], v[150:153], v[190:193], v[114:117]
	v_mfma_f32_16x16x32_bf16 v[110:113], v[158:161], v[190:193], v[110:113]
	v_mfma_f32_16x16x32_bf16 v[98:101], v[150:153], v[208:211], v[98:101]
	v_mfma_f32_16x16x32_bf16 v[90:93], v[158:161], v[208:211], v[90:93]
	v_mfma_f32_16x16x32_bf16 v[78:81], v[150:153], v[216:219], v[78:81]
	v_mfma_f32_16x16x32_bf16 v[74:77], v[158:161], v[216:219], v[74:77]
	s_setprio 0
	s_setprio 1
	v_mfma_f32_16x16x32_bf16 v[122:125], v[162:165], v[178:181], v[122:125]
	v_mfma_f32_16x16x32_bf16 v[118:121], v[170:173], v[178:181], v[118:121]
	v_mfma_f32_16x16x32_bf16 v[106:109], v[162:165], v[186:189], v[106:109]
	v_mfma_f32_16x16x32_bf16 v[102:105], v[170:173], v[186:189], v[102:105]
	v_mfma_f32_16x16x32_bf16 v[86:89], v[162:165], v[194:197], v[86:89]
	v_mfma_f32_16x16x32_bf16 v[82:85], v[170:173], v[194:197], v[82:85]
	v_mfma_f32_16x16x32_bf16 v[70:73], v[162:165], v[212:215], v[70:73]
	v_mfma_f32_16x16x32_bf16 v[66:69], v[170:173], v[212:215], v[66:69]
	v_mfma_f32_16x16x32_bf16 v[122:125], v[166:169], v[182:185], v[122:125]
	v_mfma_f32_16x16x32_bf16 v[118:121], v[174:177], v[182:185], v[118:121]
	v_mfma_f32_16x16x32_bf16 v[106:109], v[166:169], v[190:193], v[106:109]
	v_mfma_f32_16x16x32_bf16 v[102:105], v[174:177], v[190:193], v[102:105]
	v_mfma_f32_16x16x32_bf16 v[86:89], v[166:169], v[208:211], v[86:89]
	v_mfma_f32_16x16x32_bf16 v[82:85], v[174:177], v[208:211], v[82:85]
	v_mfma_f32_16x16x32_bf16 v[70:73], v[166:169], v[216:219], v[70:73]
	v_mfma_f32_16x16x32_bf16 v[66:69], v[174:177], v[216:219], v[66:69]
	s_setprio 0
	s_barrier
	s_add_i32 s54, s52, s6
	s_add_i32 m0, s54, 0xffffff80
	ds_read_b128 v[178:181], v145 offset:49152
	ds_read_b128 v[182:185], v145 offset:50176
	ds_read_b128 v[186:189], v145 offset:51200
	ds_read_b128 v[190:193], v145 offset:52224
	ds_read_b128 v[194:197], v145 offset:53248
	ds_read_b128 v[208:211], v145 offset:54272
	ds_read_b128 v[212:215], v145 offset:55296
	ds_read_b128 v[216:219], v145 offset:56320
	global_load_lds_dwordx4 v134, s[40:41] offset:128
	s_add_i32 m0, s54, 0x1f80
	s_nop 0
	global_load_lds_dwordx4 v94, s[40:41] offset:128
	s_add_i32 s54, s53, s6
	s_add_u32 s40, s40, 0x40080
	s_addc_u32 s41, s41, 0
	s_mov_b32 m0, s54
	s_nop 0
	global_load_lds_dwordx4 v134, s[40:41]
	s_add_i32 m0, s54, 0x2000
	s_nop 0
	global_load_lds_dwordx4 v94, s[40:41]
	s_add_u32 s42, s42, 0xfffc0080
	s_addc_u32 s43, s43, -1
	s_mov_b32 m0, s28
	s_nop 0
	global_load_lds_dwordx4 v134, s[42:43]
	s_mov_b32 m0, s29
	s_nop 0
	global_load_lds_dwordx4 v94, s[42:43]
	s_waitcnt vmcnt(8)
	s_waitcnt lgkmcnt(0)
	s_cmp_lg_u32 s51, 12
	s_cbranch_scc1 .Lup_nopf
	s_lshl_b32 s54, s46, 8
	s_add_i32 s54, s54, s25
	v_and_b32_e32 v232, 0x18, v143
	v_or_b32_e32 v233, s54, v97
	v_lshrrev_b32_e32 v232, 1, v232
	v_lshl_add_u32 v232, v233, 4, v232
	global_load_dword v233, v232, s[16:17]
	global_load_dword v234, v232, s[16:17] offset:256
	global_load_dword v235, v232, s[16:17] offset:512
	global_load_dword v236, v232, s[16:17] offset:768
	global_load_dword v237, v232, s[16:17] offset:2048
	global_load_dword v238, v232, s[16:17] offset:2304
	global_load_dword v239, v232, s[16:17] offset:2560
	global_load_dword v240, v232, s[16:17] offset:2816
.Lup_nopf:
	s_barrier
	s_setprio 1
	s_waitcnt lgkmcnt(0)
	v_mfma_f32_16x16x32_bf16 v[62:65], v[146:149], v[178:181], v[62:65]
	v_mfma_f32_16x16x32_bf16 v[58:61], v[154:157], v[178:181], v[58:61]
	v_mfma_f32_16x16x32_bf16 v[46:49], v[146:149], v[186:189], v[46:49]
	v_mfma_f32_16x16x32_bf16 v[42:45], v[154:157], v[186:189], v[42:45]
	v_mfma_f32_16x16x32_bf16 v[30:33], v[146:149], v[194:197], v[30:33]
	v_mfma_f32_16x16x32_bf16 v[26:29], v[154:157], v[194:197], v[26:29]
	v_mfma_f32_16x16x32_bf16 v[14:17], v[146:149], v[212:215], v[14:17]
	v_mfma_f32_16x16x32_bf16 v[10:13], v[154:157], v[212:215], v[10:13]
	v_mfma_f32_16x16x32_bf16 v[62:65], v[150:153], v[182:185], v[62:65]
	v_mfma_f32_16x16x32_bf16 v[58:61], v[158:161], v[182:185], v[58:61]
	v_mfma_f32_16x16x32_bf16 v[46:49], v[150:153], v[190:193], v[46:49]
	v_mfma_f32_16x16x32_bf16 v[42:45], v[158:161], v[190:193], v[42:45]
	v_mfma_f32_16x16x32_bf16 v[30:33], v[150:153], v[208:211], v[30:33]
	v_mfma_f32_16x16x32_bf16 v[26:29], v[158:161], v[208:211], v[26:29]
	v_mfma_f32_16x16x32_bf16 v[14:17], v[150:153], v[216:219], v[14:17]
	v_mfma_f32_16x16x32_bf16 v[10:13], v[158:161], v[216:219], v[10:13]
	s_setprio 0
	s_setprio 1
	v_mfma_f32_16x16x32_bf16 v[54:57], v[162:165], v[178:181], v[54:57]
	v_mfma_f32_16x16x32_bf16 v[50:53], v[170:173], v[178:181], v[50:53]
	v_mfma_f32_16x16x32_bf16 v[38:41], v[162:165], v[186:189], v[38:41]
	v_mfma_f32_16x16x32_bf16 v[34:37], v[170:173], v[186:189], v[34:37]
	v_mfma_f32_16x16x32_bf16 v[22:25], v[162:165], v[194:197], v[22:25]
	v_mfma_f32_16x16x32_bf16 v[18:21], v[170:173], v[194:197], v[18:21]
	v_mfma_f32_16x16x32_bf16 v[6:9], v[162:165], v[212:215], v[6:9]
	v_mfma_f32_16x16x32_bf16 v[2:5], v[170:173], v[212:215], v[2:5]
	v_mfma_f32_16x16x32_bf16 v[54:57], v[166:169], v[182:185], v[54:57]
	v_mfma_f32_16x16x32_bf16 v[50:53], v[174:177], v[182:185], v[50:53]
	v_mfma_f32_16x16x32_bf16 v[38:41], v[166:169], v[190:193], v[38:41]
	v_mfma_f32_16x16x32_bf16 v[34:37], v[174:177], v[190:193], v[34:37]
	v_mfma_f32_16x16x32_bf16 v[22:25], v[166:169], v[208:211], v[22:25]
	v_mfma_f32_16x16x32_bf16 v[18:21], v[174:177], v[208:211], v[18:21]
	v_mfma_f32_16x16x32_bf16 v[6:9], v[166:169], v[216:219], v[6:9]
	v_mfma_f32_16x16x32_bf16 v[2:5], v[174:177], v[216:219], v[2:5]
	s_setprio 0
	s_barrier
	s_add_i32 s51, s51, 2
	s_add_u32 s49, s49, 0x100
	s_addc_u32 s50, s50, 0
	s_add_u32 s38, s38, 0x100
	s_addc_u32 s39, s39, 0
	s_cmp_gt_u32 s51, 13
	s_cbranch_scc0 .LBB0_565
	s_lshl_b32 s19, s46, 8
	s_add_i32 s19, s19, s25
	v_lshl_or_b32 v184, s45, 7, v143
	s_and_b64 vcc, exec, s[10:11]
	s_cbranch_vccz .LBB0_568
	s_barrier
.LBB0_568:
	s_waitcnt vmcnt(0)
	v_mov_b32_e32 v186, v233
	v_mov_b32_e32 v187, v234
	v_mov_b32_e32 v188, v235
	v_mov_b32_e32 v189, v236
	v_mov_b32_e32 v190, v237
	v_mov_b32_e32 v191, v238
	v_mov_b32_e32 v192, v239
	v_mov_b32_e32 v193, v240
	v_permlane16_swap_b32_e32 v233, v186
	v_permlane16_swap_b32_e32 v234, v187
	v_permlane16_swap_b32_e32 v235, v188
	v_permlane16_swap_b32_e32 v236, v189
	v_permlane16_swap_b32_e32 v237, v190
	v_permlane16_swap_b32_e32 v238, v191
	v_permlane16_swap_b32_e32 v239, v192
	v_permlane16_swap_b32_e32 v240, v193
	v_add_f32_e32 v208, v233, v186
	v_add_f32_e32 v209, v234, v187
	v_add_f32_e32 v210, v235, v188
	v_add_f32_e32 v211, v236, v189
	v_add_f32_e32 v212, v237, v190
	v_add_f32_e32 v213, v238, v191
	v_add_f32_e32 v214, v239, v192
	v_add_f32_e32 v215, v240, v193
	v_mov_b32_e32 v186, v208
	v_mov_b32_e32 v187, v209
	v_mov_b32_e32 v188, v210
	v_mov_b32_e32 v189, v211
	v_mov_b32_e32 v190, v212
	v_mov_b32_e32 v191, v213
	v_mov_b32_e32 v192, v214
	v_mov_b32_e32 v193, v215
	v_permlane32_swap_b32_e32 v208, v186
	v_permlane32_swap_b32_e32 v209, v187
	v_permlane32_swap_b32_e32 v210, v188
	v_permlane32_swap_b32_e32 v211, v189
	v_permlane32_swap_b32_e32 v212, v190
	v_permlane32_swap_b32_e32 v213, v191
	v_permlane32_swap_b32_e32 v214, v192
	v_permlane32_swap_b32_e32 v215, v193
	v_add_f32_e32 v208, v208, v186
	v_add_f32_e32 v209, v209, v187
	v_add_f32_e32 v210, v210, v188
	v_add_f32_e32 v211, v211, v189
	v_add_f32_e32 v212, v212, v190
	v_add_f32_e32 v213, v213, v191
	v_add_f32_e32 v214, v214, v192
	v_add_f32_e32 v215, v215, v193
	v_fmamk_f32 v208, v208, 0x3a800000, v222
	v_fmamk_f32 v209, v209, 0x3a800000, v222
	v_fmamk_f32 v210, v210, 0x3a800000, v222
	v_fmamk_f32 v211, v211, 0x3a800000, v222
	v_fmamk_f32 v212, v212, 0x3a800000, v222
	v_fmamk_f32 v213, v213, 0x3a800000, v222
	v_fmamk_f32 v214, v214, 0x3a800000, v222
	v_fmamk_f32 v215, v215, 0x3a800000, v222
	v_rsq_f32_e32 v208, v208
	v_rsq_f32_e32 v209, v209
	v_rsq_f32_e32 v210, v210
	v_rsq_f32_e32 v211, v211
	v_rsq_f32_e32 v212, v212
	v_rsq_f32_e32 v213, v213
	v_rsq_f32_e32 v214, v214
	v_rsq_f32_e32 v215, v215
	s_ashr_i32 s21, s19, 11
	s_mul_hi_i32 s39, s21, 0x1414000
	s_mul_i32 s21, s21, 0x1414000
	v_bitop3_b32 v149, s19, v230, v97 bitop3:0xc8
	s_add_u32 s38, s4, s21
	s_addc_u32 s39, s5, s39
	v_mul_u32_u24_e32 v0, 0xb00, v149
	v_lshlrev_b32_e32 v0, 1, v0
	v_lshl_add_u32 v220, v184, 1, v0
	v_mul_f32_e32 v232, v208, v208
	v_mul_f32_e32 v233, 0xbfb8aa3b, v208
	v_mul_f32_e32 v234, v209, v209
	v_mul_f32_e32 v235, 0xbfb8aa3b, v209
	v_mul_f32_e32 v236, v210, v210
	v_mul_f32_e32 v237, 0xbfb8aa3b, v210
	v_mul_f32_e32 v238, v211, v211
	v_mul_f32_e32 v239, 0xbfb8aa3b, v211
	v_mul_f32_e32 v240, v212, v212
	v_mul_f32_e32 v241, 0xbfb8aa3b, v212
	v_mul_f32_e32 v242, v213, v213
	v_mul_f32_e32 v243, 0xbfb8aa3b, v213
	v_mul_f32_e32 v244, v214, v214
	v_mul_f32_e32 v245, 0xbfb8aa3b, v214
	v_mul_f32_e32 v246, v215, v215
	v_mul_f32_e32 v247, 0xbfb8aa3b, v215
	v_pk_mul_f32 v[208:209], v[130:131], v[232:233] op_sel:[0,1] op_sel_hi:[1,1]
	v_pk_mul_f32 v[210:211], v[132:133], v[232:233] op_sel:[0,1] op_sel_hi:[1,1]
	v_pk_mul_f32 v[212:213], v[126:127], v[232:233] op_sel:[0,1] op_sel_hi:[1,1]
	v_pk_mul_f32 v[214:215], v[128:129], v[232:233] op_sel:[0,1] op_sel_hi:[1,1]
	v_exp_f32_e32 v208, v208
	v_exp_f32_e32 v209, v209
	v_exp_f32_e32 v210, v210
	v_exp_f32_e32 v211, v211
	v_exp_f32_e32 v212, v212
	v_exp_f32_e32 v213, v213
	v_exp_f32_e32 v214, v214
	v_exp_f32_e32 v215, v215
	v_pk_add_f32 v[208:209], v[208:209], 1.0 op_sel_hi:[1,0]
	v_pk_add_f32 v[210:211], v[210:211], 1.0 op_sel_hi:[1,0]
	v_pk_add_f32 v[212:213], v[212:213], 1.0 op_sel_hi:[1,0]
	v_pk_add_f32 v[214:215], v[214:215], 1.0 op_sel_hi:[1,0]
	v_rcp_f32_e32 v208, v208
	v_rcp_f32_e32 v209, v209
	v_rcp_f32_e32 v210, v210
	v_rcp_f32_e32 v211, v211
	v_rcp_f32_e32 v212, v212
	v_rcp_f32_e32 v213, v213
	v_rcp_f32_e32 v214, v214
	v_rcp_f32_e32 v215, v215
	v_pk_mul_f32 v[130:131], v[130:131], v[122:123]
	v_pk_mul_f32 v[132:133], v[132:133], v[124:125]
	v_pk_mul_f32 v[126:127], v[126:127], v[118:119]
	v_pk_mul_f32 v[128:129], v[128:129], v[120:121]
	v_pk_mul_f32 v[208:209], v[208:209], v[232:233] op_sel_hi:[1,0]
	v_pk_mul_f32 v[210:211], v[210:211], v[232:233] op_sel_hi:[1,0]
	v_pk_mul_f32 v[212:213], v[212:213], v[232:233] op_sel_hi:[1,0]
	v_pk_mul_f32 v[214:215], v[214:215], v[232:233] op_sel_hi:[1,0]
	v_pk_mul_f32 v[130:131], v[130:131], v[208:209]
	v_pk_mul_f32 v[132:133], v[132:133], v[210:211]
	v_pk_mul_f32 v[126:127], v[126:127], v[212:213]
	v_pk_mul_f32 v[128:129], v[128:129], v[214:215]
	v_cvt_pk_bf16_f32 v216, v130, v131
	v_cvt_pk_bf16_f32 v217, v132, v133
	v_cvt_pk_bf16_f32 v218, v126, v127
	v_cvt_pk_bf16_f32 v219, v128, v129
	global_store_dwordx4 v220, v[216:219], s[38:39]
	v_pk_mul_f32 v[208:209], v[114:115], v[234:235] op_sel:[0,1] op_sel_hi:[1,1]
	v_pk_mul_f32 v[210:211], v[116:117], v[234:235] op_sel:[0,1] op_sel_hi:[1,1]
	v_pk_mul_f32 v[212:213], v[110:111], v[234:235] op_sel:[0,1] op_sel_hi:[1,1]
	v_pk_mul_f32 v[214:215], v[112:113], v[234:235] op_sel:[0,1] op_sel_hi:[1,1]
	v_exp_f32_e32 v208, v208
	v_exp_f32_e32 v209, v209
	v_exp_f32_e32 v210, v210
	v_exp_f32_e32 v211, v211
	v_exp_f32_e32 v212, v212
	v_exp_f32_e32 v213, v213
	v_exp_f32_e32 v214, v214
	v_exp_f32_e32 v215, v215
	v_pk_add_f32 v[208:209], v[208:209], 1.0 op_sel_hi:[1,0]
	v_pk_add_f32 v[210:211], v[210:211], 1.0 op_sel_hi:[1,0]
	v_pk_add_f32 v[212:213], v[212:213], 1.0 op_sel_hi:[1,0]
	v_pk_add_f32 v[214:215], v[214:215], 1.0 op_sel_hi:[1,0]
	v_rcp_f32_e32 v208, v208
	v_rcp_f32_e32 v209, v209
	v_rcp_f32_e32 v210, v210
	v_rcp_f32_e32 v211, v211
	v_rcp_f32_e32 v212, v212
	v_rcp_f32_e32 v213, v213
	v_rcp_f32_e32 v214, v214
	v_rcp_f32_e32 v215, v215
	v_pk_mul_f32 v[114:115], v[114:115], v[106:107]
	v_pk_mul_f32 v[116:117], v[116:117], v[108:109]
	v_pk_mul_f32 v[110:111], v[110:111], v[102:103]
	v_pk_mul_f32 v[112:113], v[112:113], v[104:105]
	v_pk_mul_f32 v[208:209], v[208:209], v[234:235] op_sel_hi:[1,0]
	v_pk_mul_f32 v[210:211], v[210:211], v[234:235] op_sel_hi:[1,0]
	v_pk_mul_f32 v[212:213], v[212:213], v[234:235] op_sel_hi:[1,0]
	v_pk_mul_f32 v[214:215], v[214:215], v[234:235] op_sel_hi:[1,0]
	v_pk_mul_f32 v[114:115], v[114:115], v[208:209]
	v_pk_mul_f32 v[116:117], v[116:117], v[210:211]
	v_pk_mul_f32 v[110:111], v[110:111], v[212:213]
	v_pk_mul_f32 v[112:113], v[112:113], v[214:215]
	v_cvt_pk_bf16_f32 v248, v114, v115
	v_cvt_pk_bf16_f32 v249, v116, v117
	v_cvt_pk_bf16_f32 v250, v110, v111
	v_cvt_pk_bf16_f32 v251, v112, v113
	v_add_u32_e32 v221, 0x16000, v220
	global_store_dwordx4 v221, v[248:251], s[38:39]
	v_pk_mul_f32 v[208:209], v[98:99], v[236:237] op_sel:[0,1] op_sel_hi:[1,1]
	v_pk_mul_f32 v[210:211], v[100:101], v[236:237] op_sel:[0,1] op_sel_hi:[1,1]
	v_pk_mul_f32 v[212:213], v[90:91], v[236:237] op_sel:[0,1] op_sel_hi:[1,1]
	v_pk_mul_f32 v[214:215], v[92:93], v[236:237] op_sel:[0,1] op_sel_hi:[1,1]
	v_exp_f32_e32 v208, v208
	v_exp_f32_e32 v209, v209
	v_exp_f32_e32 v210, v210
	v_exp_f32_e32 v211, v211
	v_exp_f32_e32 v212, v212
	v_exp_f32_e32 v213, v213
	v_exp_f32_e32 v214, v214
	v_exp_f32_e32 v215, v215
	v_pk_add_f32 v[208:209], v[208:209], 1.0 op_sel_hi:[1,0]
	v_pk_add_f32 v[210:211], v[210:211], 1.0 op_sel_hi:[1,0]
	v_pk_add_f32 v[212:213], v[212:213], 1.0 op_sel_hi:[1,0]
	v_pk_add_f32 v[214:215], v[214:215], 1.0 op_sel_hi:[1,0]
	v_rcp_f32_e32 v208, v208
	v_rcp_f32_e32 v209, v209
	v_rcp_f32_e32 v210, v210
	v_rcp_f32_e32 v211, v211
	v_rcp_f32_e32 v212, v212
	v_rcp_f32_e32 v213, v213
	v_rcp_f32_e32 v214, v214
	v_rcp_f32_e32 v215, v215
	v_pk_mul_f32 v[98:99], v[98:99], v[86:87]
	v_pk_mul_f32 v[100:101], v[100:101], v[88:89]
	v_pk_mul_f32 v[90:91], v[90:91], v[82:83]
	v_pk_mul_f32 v[92:93], v[92:93], v[84:85]
	v_pk_mul_f32 v[208:209], v[208:209], v[236:237] op_sel_hi:[1,0]
	v_pk_mul_f32 v[210:211], v[210:211], v[236:237] op_sel_hi:[1,0]
	v_pk_mul_f32 v[212:213], v[212:213], v[236:237] op_sel_hi:[1,0]
	v_pk_mul_f32 v[214:215], v[214:215], v[236:237] op_sel_hi:[1,0]
	v_pk_mul_f32 v[98:99], v[98:99], v[208:209]
	v_pk_mul_f32 v[100:101], v[100:101], v[210:211]
	v_pk_mul_f32 v[90:91], v[90:91], v[212:213]
	v_pk_mul_f32 v[92:93], v[92:93], v[214:215]
	v_cvt_pk_bf16_f32 v216, v98, v99
	v_cvt_pk_bf16_f32 v217, v100, v101
	v_cvt_pk_bf16_f32 v218, v90, v91
	v_cvt_pk_bf16_f32 v219, v92, v93
	v_add_u32_e32 v221, 0x2c000, v220
	global_store_dwordx4 v221, v[216:219], s[38:39]
	v_pk_mul_f32 v[208:209], v[78:79], v[238:239] op_sel:[0,1] op_sel_hi:[1,1]
	v_pk_mul_f32 v[210:211], v[80:81], v[238:239] op_sel:[0,1] op_sel_hi:[1,1]
	v_pk_mul_f32 v[212:213], v[74:75], v[238:239] op_sel:[0,1] op_sel_hi:[1,1]
	v_pk_mul_f32 v[214:215], v[76:77], v[238:239] op_sel:[0,1] op_sel_hi:[1,1]
	v_exp_f32_e32 v208, v208
	v_exp_f32_e32 v209, v209
	v_exp_f32_e32 v210, v210
	v_exp_f32_e32 v211, v211
	v_exp_f32_e32 v212, v212
	v_exp_f32_e32 v213, v213
	v_exp_f32_e32 v214, v214
	v_exp_f32_e32 v215, v215
	v_pk_add_f32 v[208:209], v[208:209], 1.0 op_sel_hi:[1,0]
	v_pk_add_f32 v[210:211], v[210:211], 1.0 op_sel_hi:[1,0]
	v_pk_add_f32 v[212:213], v[212:213], 1.0 op_sel_hi:[1,0]
	v_pk_add_f32 v[214:215], v[214:215], 1.0 op_sel_hi:[1,0]
	v_rcp_f32_e32 v208, v208
	v_rcp_f32_e32 v209, v209
	v_rcp_f32_e32 v210, v210
	v_rcp_f32_e32 v211, v211
	v_rcp_f32_e32 v212, v212
	v_rcp_f32_e32 v213, v213
	v_rcp_f32_e32 v214, v214
	v_rcp_f32_e32 v215, v215
	v_pk_mul_f32 v[78:79], v[78:79], v[70:71]
	v_pk_mul_f32 v[80:81], v[80:81], v[72:73]
	v_pk_mul_f32 v[74:75], v[74:75], v[66:67]
	v_pk_mul_f32 v[76:77], v[76:77], v[68:69]
	v_pk_mul_f32 v[208:209], v[208:209], v[238:239] op_sel_hi:[1,0]
	v_pk_mul_f32 v[210:211], v[210:211], v[238:239] op_sel_hi:[1,0]
	v_pk_mul_f32 v[212:213], v[212:213], v[238:239] op_sel_hi:[1,0]
	v_pk_mul_f32 v[214:215], v[214:215], v[238:239] op_sel_hi:[1,0]
	v_pk_mul_f32 v[78:79], v[78:79], v[208:209]
	v_pk_mul_f32 v[80:81], v[80:81], v[210:211]
	v_pk_mul_f32 v[74:75], v[74:75], v[212:213]
	v_pk_mul_f32 v[76:77], v[76:77], v[214:215]
	v_cvt_pk_bf16_f32 v248, v78, v79
	v_cvt_pk_bf16_f32 v249, v80, v81
	v_cvt_pk_bf16_f32 v250, v74, v75
	v_cvt_pk_bf16_f32 v251, v76, v77
	v_add_u32_e32 v221, 0x42000, v220
	global_store_dwordx4 v221, v[248:251], s[38:39]
	v_pk_mul_f32 v[208:209], v[62:63], v[240:241] op_sel:[0,1] op_sel_hi:[1,1]
	v_pk_mul_f32 v[210:211], v[64:65], v[240:241] op_sel:[0,1] op_sel_hi:[1,1]
	v_pk_mul_f32 v[212:213], v[58:59], v[240:241] op_sel:[0,1] op_sel_hi:[1,1]
	v_pk_mul_f32 v[214:215], v[60:61], v[240:241] op_sel:[0,1] op_sel_hi:[1,1]
	v_exp_f32_e32 v208, v208
	v_exp_f32_e32 v209, v209
	v_exp_f32_e32 v210, v210
	v_exp_f32_e32 v211, v211
	v_exp_f32_e32 v212, v212
	v_exp_f32_e32 v213, v213
	v_exp_f32_e32 v214, v214
	v_exp_f32_e32 v215, v215
	v_pk_add_f32 v[208:209], v[208:209], 1.0 op_sel_hi:[1,0]
	v_pk_add_f32 v[210:211], v[210:211], 1.0 op_sel_hi:[1,0]
	v_pk_add_f32 v[212:213], v[212:213], 1.0 op_sel_hi:[1,0]
	v_pk_add_f32 v[214:215], v[214:215], 1.0 op_sel_hi:[1,0]
	v_rcp_f32_e32 v208, v208
	v_rcp_f32_e32 v209, v209
	v_rcp_f32_e32 v210, v210
	v_rcp_f32_e32 v211, v211
	v_rcp_f32_e32 v212, v212
	v_rcp_f32_e32 v213, v213
	v_rcp_f32_e32 v214, v214
	v_rcp_f32_e32 v215, v215
	v_pk_mul_f32 v[62:63], v[62:63], v[54:55]
	v_pk_mul_f32 v[64:65], v[64:65], v[56:57]
	v_pk_mul_f32 v[58:59], v[58:59], v[50:51]
	v_pk_mul_f32 v[60:61], v[60:61], v[52:53]
	v_pk_mul_f32 v[208:209], v[208:209], v[240:241] op_sel_hi:[1,0]
	v_pk_mul_f32 v[210:211], v[210:211], v[240:241] op_sel_hi:[1,0]
	v_pk_mul_f32 v[212:213], v[212:213], v[240:241] op_sel_hi:[1,0]
	v_pk_mul_f32 v[214:215], v[214:215], v[240:241] op_sel_hi:[1,0]
	v_pk_mul_f32 v[62:63], v[62:63], v[208:209]
	v_pk_mul_f32 v[64:65], v[64:65], v[210:211]
	v_pk_mul_f32 v[58:59], v[58:59], v[212:213]
	v_pk_mul_f32 v[60:61], v[60:61], v[214:215]
	v_cvt_pk_bf16_f32 v216, v62, v63
	v_cvt_pk_bf16_f32 v217, v64, v65
	v_cvt_pk_bf16_f32 v218, v58, v59
	v_cvt_pk_bf16_f32 v219, v60, v61
	v_add_u32_e32 v221, 0xb0000, v220
	global_store_dwordx4 v221, v[216:219], s[38:39]
	v_pk_mul_f32 v[208:209], v[46:47], v[242:243] op_sel:[0,1] op_sel_hi:[1,1]
	v_pk_mul_f32 v[210:211], v[48:49], v[242:243] op_sel:[0,1] op_sel_hi:[1,1]
	v_pk_mul_f32 v[212:213], v[42:43], v[242:243] op_sel:[0,1] op_sel_hi:[1,1]
	v_pk_mul_f32 v[214:215], v[44:45], v[242:243] op_sel:[0,1] op_sel_hi:[1,1]
	v_exp_f32_e32 v208, v208
	v_exp_f32_e32 v209, v209
	v_exp_f32_e32 v210, v210
	v_exp_f32_e32 v211, v211
	v_exp_f32_e32 v212, v212
	v_exp_f32_e32 v213, v213
	v_exp_f32_e32 v214, v214
	v_exp_f32_e32 v215, v215
	v_pk_add_f32 v[208:209], v[208:209], 1.0 op_sel_hi:[1,0]
	v_pk_add_f32 v[210:211], v[210:211], 1.0 op_sel_hi:[1,0]
	v_pk_add_f32 v[212:213], v[212:213], 1.0 op_sel_hi:[1,0]
	v_pk_add_f32 v[214:215], v[214:215], 1.0 op_sel_hi:[1,0]
	v_rcp_f32_e32 v208, v208
	v_rcp_f32_e32 v209, v209
	v_rcp_f32_e32 v210, v210
	v_rcp_f32_e32 v211, v211
	v_rcp_f32_e32 v212, v212
	v_rcp_f32_e32 v213, v213
	v_rcp_f32_e32 v214, v214
	v_rcp_f32_e32 v215, v215
	v_pk_mul_f32 v[46:47], v[46:47], v[38:39]
	v_pk_mul_f32 v[48:49], v[48:49], v[40:41]
	v_pk_mul_f32 v[42:43], v[42:43], v[34:35]
	v_pk_mul_f32 v[44:45], v[44:45], v[36:37]
	v_pk_mul_f32 v[208:209], v[208:209], v[242:243] op_sel_hi:[1,0]
	v_pk_mul_f32 v[210:211], v[210:211], v[242:243] op_sel_hi:[1,0]
	v_pk_mul_f32 v[212:213], v[212:213], v[242:243] op_sel_hi:[1,0]
	v_pk_mul_f32 v[214:215], v[214:215], v[242:243] op_sel_hi:[1,0]
	v_pk_mul_f32 v[46:47], v[46:47], v[208:209]
	v_pk_mul_f32 v[48:49], v[48:49], v[210:211]
	v_pk_mul_f32 v[42:43], v[42:43], v[212:213]
	v_pk_mul_f32 v[44:45], v[44:45], v[214:215]
	v_cvt_pk_bf16_f32 v248, v46, v47
	v_cvt_pk_bf16_f32 v249, v48, v49
	v_cvt_pk_bf16_f32 v250, v42, v43
	v_cvt_pk_bf16_f32 v251, v44, v45
	v_add_u32_e32 v221, 0xc6000, v220
	global_store_dwordx4 v221, v[248:251], s[38:39]
	v_pk_mul_f32 v[208:209], v[30:31], v[244:245] op_sel:[0,1] op_sel_hi:[1,1]
	v_pk_mul_f32 v[210:211], v[32:33], v[244:245] op_sel:[0,1] op_sel_hi:[1,1]
	v_pk_mul_f32 v[212:213], v[26:27], v[244:245] op_sel:[0,1] op_sel_hi:[1,1]
	v_pk_mul_f32 v[214:215], v[28:29], v[244:245] op_sel:[0,1] op_sel_hi:[1,1]
	v_exp_f32_e32 v208, v208
	v_exp_f32_e32 v209, v209
	v_exp_f32_e32 v210, v210
	v_exp_f32_e32 v211, v211
	v_exp_f32_e32 v212, v212
	v_exp_f32_e32 v213, v213
	v_exp_f32_e32 v214, v214
	v_exp_f32_e32 v215, v215
	v_pk_add_f32 v[208:209], v[208:209], 1.0 op_sel_hi:[1,0]
	v_pk_add_f32 v[210:211], v[210:211], 1.0 op_sel_hi:[1,0]
	v_pk_add_f32 v[212:213], v[212:213], 1.0 op_sel_hi:[1,0]
	v_pk_add_f32 v[214:215], v[214:215], 1.0 op_sel_hi:[1,0]
	v_rcp_f32_e32 v208, v208
	v_rcp_f32_e32 v209, v209
	v_rcp_f32_e32 v210, v210
	v_rcp_f32_e32 v211, v211
	v_rcp_f32_e32 v212, v212
	v_rcp_f32_e32 v213, v213
	v_rcp_f32_e32 v214, v214
	v_rcp_f32_e32 v215, v215
	v_pk_mul_f32 v[30:31], v[30:31], v[22:23]
	v_pk_mul_f32 v[32:33], v[32:33], v[24:25]
	v_pk_mul_f32 v[26:27], v[26:27], v[18:19]
	v_pk_mul_f32 v[28:29], v[28:29], v[20:21]
	v_pk_mul_f32 v[208:209], v[208:209], v[244:245] op_sel_hi:[1,0]
	v_pk_mul_f32 v[210:211], v[210:211], v[244:245] op_sel_hi:[1,0]
	v_pk_mul_f32 v[212:213], v[212:213], v[244:245] op_sel_hi:[1,0]
	v_pk_mul_f32 v[214:215], v[214:215], v[244:245] op_sel_hi:[1,0]
	v_pk_mul_f32 v[30:31], v[30:31], v[208:209]
	v_pk_mul_f32 v[32:33], v[32:33], v[210:211]
	v_pk_mul_f32 v[26:27], v[26:27], v[212:213]
	v_pk_mul_f32 v[28:29], v[28:29], v[214:215]
	v_cvt_pk_bf16_f32 v216, v30, v31
	v_cvt_pk_bf16_f32 v217, v32, v33
	v_cvt_pk_bf16_f32 v218, v26, v27
	v_cvt_pk_bf16_f32 v219, v28, v29
	v_add_u32_e32 v221, 0xdc000, v220
	global_store_dwordx4 v221, v[216:219], s[38:39]
	v_pk_mul_f32 v[208:209], v[14:15], v[246:247] op_sel:[0,1] op_sel_hi:[1,1]
	v_pk_mul_f32 v[210:211], v[16:17], v[246:247] op_sel:[0,1] op_sel_hi:[1,1]
	v_pk_mul_f32 v[212:213], v[10:11], v[246:247] op_sel:[0,1] op_sel_hi:[1,1]
	v_pk_mul_f32 v[214:215], v[12:13], v[246:247] op_sel:[0,1] op_sel_hi:[1,1]
	v_exp_f32_e32 v208, v208
	v_exp_f32_e32 v209, v209
	v_exp_f32_e32 v210, v210
	v_exp_f32_e32 v211, v211
	v_exp_f32_e32 v212, v212
	v_exp_f32_e32 v213, v213
	v_exp_f32_e32 v214, v214
	v_exp_f32_e32 v215, v215
	v_pk_add_f32 v[208:209], v[208:209], 1.0 op_sel_hi:[1,0]
	v_pk_add_f32 v[210:211], v[210:211], 1.0 op_sel_hi:[1,0]
	v_pk_add_f32 v[212:213], v[212:213], 1.0 op_sel_hi:[1,0]
	v_pk_add_f32 v[214:215], v[214:215], 1.0 op_sel_hi:[1,0]
	v_rcp_f32_e32 v208, v208
	v_rcp_f32_e32 v209, v209
	v_rcp_f32_e32 v210, v210
	v_rcp_f32_e32 v211, v211
	v_rcp_f32_e32 v212, v212
	v_rcp_f32_e32 v213, v213
	v_rcp_f32_e32 v214, v214
	v_rcp_f32_e32 v215, v215
	v_pk_mul_f32 v[14:15], v[14:15], v[6:7]
	v_pk_mul_f32 v[16:17], v[16:17], v[8:9]
	v_pk_mul_f32 v[10:11], v[10:11], v[2:3]
	v_pk_mul_f32 v[12:13], v[12:13], v[4:5]
	v_pk_mul_f32 v[208:209], v[208:209], v[246:247] op_sel_hi:[1,0]
	v_pk_mul_f32 v[210:211], v[210:211], v[246:247] op_sel_hi:[1,0]
	v_pk_mul_f32 v[212:213], v[212:213], v[246:247] op_sel_hi:[1,0]
	v_pk_mul_f32 v[214:215], v[214:215], v[246:247] op_sel_hi:[1,0]
	v_pk_mul_f32 v[14:15], v[14:15], v[208:209]
	v_pk_mul_f32 v[16:17], v[16:17], v[210:211]
	v_pk_mul_f32 v[10:11], v[10:11], v[212:213]
	v_pk_mul_f32 v[12:13], v[12:13], v[214:215]
	v_cvt_pk_bf16_f32 v248, v14, v15
	v_cvt_pk_bf16_f32 v249, v16, v17
	v_cvt_pk_bf16_f32 v250, v10, v11
	v_cvt_pk_bf16_f32 v251, v12, v13
	v_add_u32_e32 v221, 0xf2000, v220
	global_store_dwordx4 v221, v[248:251], s[38:39]
	s_mov_b32 s21, 0x16000
	s_mov_b32 s40, 0x2c000
	s_mov_b32 s19, 0x1414000
	s_andn2_b64 vcc, exec, s[36:37]
	s_mov_b64 s[36:37], -1
	s_cbranch_vccnz .LBB0_561
	s_andn2_b64 vcc, exec, s[0:1]
	s_cbranch_vccnz .LBB0_560
	s_barrier
	s_branch .LBB0_560
